# v31 + nt hint on the f32 weight loads of the weight-conversion items (read once per launch)
# speedup vs baseline: 1.0148x; 1.0148x over previous
; #define LAS __attribute__((address_space(3)))
; DI unsigned pk2(float lo, float hi) { f32x2 v = {lo, hi}; bf16x2_t b = __builtin_convertvector(v, bf16x2_t); return __builtin_bit_cast(unsigned, b); }
; DI void transpose_item_wide(const float* W, int ldw, int K, int src0, bf16* WT, int n0, int k0, LAS float* scr, int lane) {
;     const int c4 = lane & 7, kr = lane >> 3;
; #pragma unroll
;     for (int i = 0; i < 8; ++i) { const int kk = kr + 8 * i; const f32x4 v = *(const f32x4*)(W + (size_t)(k0 + kk) * ldw + src0 + 4 * c4);
;         LAS float* d = scr + kk * 33 + 4 * c4; d[0] = v.x; d[1] = v.y; d[2] = v.z; d[3] = v.w; }
;     asm volatile("s_waitcnt lgkmcnt(0)" ::: "memory");
;     const int c = lane & 7;
; #pragma unroll
;     for (int j = 0; j < 4; ++j) {
;         const int n = (lane >> 3) + 8 * j; const LAS float* sp = scr + (8 * c) * 33 + n;
;         u32x4 o; o.x = pk2(sp[0 * 33], sp[1 * 33]); o.y = pk2(sp[2 * 33], sp[3 * 33]); o.z = pk2(sp[4 * 33], sp[5 * 33]); o.w = pk2(sp[6 * 33], sp[7 * 33]);
;         *(u32x4*)(WT + (size_t)(n0 + n) * K + k0 + 8 * c) = o;
;     }
;     asm volatile("s_waitcnt lgkmcnt(0)" ::: "memory");
; }
; DI void convw_phase(const Args& A, int l, LAS unsigned char* lds, int tid, int bid, int G) {
;     ...
;         { const int kb = r / 32, nb = r % 32;
;           transpose_item_wide(A.in[I_WOUT] + (size_t)l * DM * DM, DM, DM, nb * 32, wout, nb * 32, kb * 64, scr, lane); }
.LBB0_246:
	s_movk_i32 s2, 0x15ff
	v_cmp_lt_i32_e32 vcc, s2, v80
	s_and_saveexec_b64 s[2:3], vcc
	s_xor_b64 s[8:9], exec, s[2:3]
	s_cbranch_execz .LBB0_268
	s_movk_i32 s2, 0x20ff
	v_cmp_lt_u32_e32 vcc, s2, v80
	s_and_saveexec_b64 s[2:3], vcc
	s_xor_b64 s[2:3], exec, s[2:3]
	s_cbranch_execz .LBB0_265
	s_movk_i32 s14, 0x27ff
	v_cmp_lt_u32_e32 vcc, s14, v80
	s_and_saveexec_b64 s[14:15], vcc
	s_xor_b64 s[14:15], exec, s[14:15]
	s_cbranch_execz .LBB0_250
	v_lshlrev_b32_e32 v0, 5, v80
	v_and_b32_e32 v2, 0x3e0, v0
	v_lshlrev_b32_e32 v0, 1, v80
	v_and_b32_e32 v0, 0x7fffffc0, v0
	v_add_u32_e32 v0, 0xffffb000, v0
	v_lshlrev_b32_e32 v146, 2, v2
	v_lshl_add_u64 v[18:19], v[16:17], 0, v[146:147]
	v_or_b32_e32 v146, v0, v7
	v_lshlrev_b64 v[32:33], 12, v[146:147]
	v_lshl_add_u64 v[32:33], v[18:19], 0, v[32:33]
	global_load_dwordx4 v[96:99], v[32:33], off nt
	v_or_b32_e32 v146, v0, v20
	v_lshlrev_b64 v[128:129], 12, v[146:147]
	v_lshl_add_u64 v[130:131], v[18:19], 0, v[128:129]
	global_load_dwordx4 v[100:103], v[130:131], off nt
	v_or_b32_e32 v146, v0, v21
	v_lshlrev_b64 v[132:133], 12, v[146:147]
	v_lshl_add_u64 v[134:135], v[18:19], 0, v[132:133]
	global_load_dwordx4 v[104:107], v[134:135], off nt
	v_or_b32_e32 v146, v0, v22
	v_lshlrev_b64 v[136:137], 12, v[146:147]
	v_lshl_add_u64 v[138:139], v[18:19], 0, v[136:137]
	global_load_dwordx4 v[108:111], v[138:139], off nt
	v_or_b32_e32 v146, v0, v23
	v_lshlrev_b64 v[140:141], 12, v[146:147]
	v_lshl_add_u64 v[142:143], v[18:19], 0, v[140:141]
	global_load_dwordx4 v[112:115], v[142:143], off nt
	v_or_b32_e32 v146, v0, v24
	v_lshlrev_b64 v[160:161], 12, v[146:147]
	v_lshl_add_u64 v[162:163], v[18:19], 0, v[160:161]
	global_load_dwordx4 v[116:119], v[162:163], off nt
	v_or_b32_e32 v146, v0, v25
	v_lshlrev_b64 v[164:165], 12, v[146:147]
	v_lshl_add_u64 v[166:167], v[18:19], 0, v[164:165]
	global_load_dwordx4 v[120:123], v[166:167], off nt
	v_or_b32_e32 v146, v0, v26
	v_lshlrev_b64 v[168:169], 12, v[146:147]
	v_lshl_add_u64 v[170:171], v[18:19], 0, v[168:169]
	global_load_dwordx4 v[124:127], v[170:171], off nt
	v_add_u32_e32 v1, v11, v13
	v_add_u32_e32 v3, 0x420, v1
	s_waitcnt vmcnt(7)
	ds_write2_b32 v1, v96, v97 offset1:1
	ds_write2_b32 v1, v98, v99 offset0:2 offset1:3
	s_waitcnt vmcnt(6)
	ds_write2_b32 v3, v100, v101 offset1:1
	v_add_u32_e32 v3, 0x428, v1
	ds_write2_b32 v3, v102, v103 offset1:1
	v_add_u32_e32 v3, 0x840, v1
	s_waitcnt vmcnt(5)
	ds_write2_b32 v3, v104, v105 offset1:1
	v_add_u32_e32 v3, 0x848, v1
	ds_write2_b32 v3, v106, v107 offset1:1
	v_add_u32_e32 v3, 0xc60, v1
	s_waitcnt vmcnt(4)
	ds_write2_b32 v3, v108, v109 offset1:1
	v_add_u32_e32 v3, 0xc68, v1
	ds_write2_b32 v3, v110, v111 offset1:1
	v_add_u32_e32 v3, 0x1080, v1
	s_waitcnt vmcnt(3)
	ds_write2_b32 v3, v112, v113 offset1:1
	v_add_u32_e32 v3, 0x1088, v1
	ds_write2_b32 v3, v114, v115 offset1:1
	v_add_u32_e32 v3, 0x14a0, v1
	s_waitcnt vmcnt(2)
	ds_write2_b32 v3, v116, v117 offset1:1
	v_add_u32_e32 v3, 0x14a8, v1
	ds_write2_b32 v3, v118, v119 offset1:1
	v_add_u32_e32 v3, 0x18c0, v1
	s_waitcnt vmcnt(1)
	ds_write2_b32 v3, v120, v121 offset1:1
	v_add_u32_e32 v3, 0x18c8, v1
	ds_write2_b32 v3, v122, v123 offset1:1
	v_add_u32_e32 v3, 0x1ce0, v1
	v_add_u32_e32 v1, 0x1ce8, v1
	s_waitcnt vmcnt(0)
	ds_write2_b32 v3, v124, v125 offset1:1
	ds_write2_b32 v1, v126, v127 offset1:1
	s_waitcnt lgkmcnt(0)
	ds_read2_b32 v[18:19], v27 offset0:33 offset1:41
	ds_read2_b32 v[36:37], v27 offset1:8
	ds_read2_b32 v[38:39], v27 offset0:66 offset1:74
	ds_read2_b32 v[40:41], v27 offset0:99 offset1:107
	ds_read2_b32 v[42:43], v27 offset0:132 offset1:140
	ds_read2_b32 v[44:45], v27 offset0:165 offset1:173
	ds_read2_b32 v[46:47], v27 offset0:198 offset1:206
	ds_read2_b32 v[48:49], v27 offset0:231 offset1:239
	v_mov_b32_e32 v1, v147
	v_or_b32_e32 v3, v2, v7
	v_lshl_add_u64 v[0:1], v[0:1], 1, v[8:9]
	v_lshlrev_b32_e32 v146, 11, v3
	v_or_b32_e32 v3, v2, v20
	s_waitcnt lgkmcnt(6)
	v_cvt_pk_bf16_f32 v32, v36, v18
	s_waitcnt lgkmcnt(4)
	v_cvt_pk_bf16_f32 v33, v38, v40
	s_waitcnt lgkmcnt(2)
	v_cvt_pk_bf16_f32 v34, v42, v44
	s_waitcnt lgkmcnt(0)
	v_cvt_pk_bf16_f32 v35, v46, v48
	v_lshl_add_u64 v[50:51], v[0:1], 0, v[146:147]
	v_lshlrev_b32_e32 v146, 11, v3
	global_store_dwordx4 v[50:51], v[32:35], off
	v_or_b32_e32 v3, v2, v21
	v_or_b32_e32 v2, v2, v22
	v_cvt_pk_bf16_f32 v32, v37, v19
	v_cvt_pk_bf16_f32 v33, v39, v41
	v_cvt_pk_bf16_f32 v34, v43, v45
	v_cvt_pk_bf16_f32 v35, v47, v49
	v_lshl_add_u64 v[18:19], v[0:1], 0, v[146:147]
	global_store_dwordx4 v[18:19], v[32:35], off
	ds_read2_b32 v[18:19], v27 offset0:49 offset1:57
	ds_read2_b32 v[36:37], v27 offset0:16 offset1:24
	ds_read2_b32 v[38:39], v27 offset0:82 offset1:90
	ds_read2_b32 v[40:41], v27 offset0:115 offset1:123
	ds_read2_b32 v[42:43], v27 offset0:148 offset1:156
	ds_read2_b32 v[44:45], v27 offset0:181 offset1:189
	ds_read2_b32 v[46:47], v27 offset0:214 offset1:222
	ds_read2_b32 v[48:49], v27 offset0:247 offset1:255
	v_lshlrev_b32_e32 v146, 11, v3
	s_waitcnt lgkmcnt(6)
	v_cvt_pk_bf16_f32 v32, v36, v18
	s_waitcnt lgkmcnt(4)
	v_cvt_pk_bf16_f32 v33, v38, v40
	s_waitcnt lgkmcnt(2)
	v_cvt_pk_bf16_f32 v34, v42, v44
	s_waitcnt lgkmcnt(0)
	v_cvt_pk_bf16_f32 v35, v46, v48
	v_lshl_add_u64 v[50:51], v[0:1], 0, v[146:147]
	v_lshlrev_b32_e32 v146, 11, v2
	global_store_dwordx4 v[50:51], v[32:35], off
	v_lshl_add_u64 v[0:1], v[0:1], 0, v[146:147]
	s_nop 0
	v_cvt_pk_bf16_f32 v32, v37, v19
	v_cvt_pk_bf16_f32 v33, v39, v41
	v_cvt_pk_bf16_f32 v34, v43, v45
	v_cvt_pk_bf16_f32 v35, v47, v49
	global_store_dwordx4 v[0:1], v[32:35], off
	s_waitcnt lgkmcnt(0)

; #define LAS __attribute__((address_space(3)))
; DI unsigned pk2(float lo, float hi) { f32x2 v = {lo, hi}; bf16x2_t b = __builtin_convertvector(v, bf16x2_t); return __builtin_bit_cast(unsigned, b); }
; DI void transpose_item_wide(const float* W, int ldw, int K, int src0, bf16* WT, int n0, int k0, LAS float* scr, int lane) {
;     const int c4 = lane & 7, kr = lane >> 3;
; #pragma unroll
;     for (int i = 0; i < 8; ++i) { const int kk = kr + 8 * i; const f32x4 v = *(const f32x4*)(W + (size_t)(k0 + kk) * ldw + src0 + 4 * c4);
;         LAS float* d = scr + kk * 33 + 4 * c4; d[0] = v.x; d[1] = v.y; d[2] = v.z; d[3] = v.w; }
;     asm volatile("s_waitcnt lgkmcnt(0)" ::: "memory");
;     const int c = lane & 7;
; #pragma unroll
;     for (int j = 0; j < 4; ++j) {
;         const int n = (lane >> 3) + 8 * j; const LAS float* sp = scr + (8 * c) * 33 + n;
;         u32x4 o; o.x = pk2(sp[0 * 33], sp[1 * 33]); o.y = pk2(sp[2 * 33], sp[3 * 33]); o.z = pk2(sp[4 * 33], sp[5 * 33]); o.w = pk2(sp[6 * 33], sp[7 * 33]);
;         *(u32x4*)(WT + (size_t)(n0 + n) * K + k0 + 8 * c) = o;
;     }
;     asm volatile("s_waitcnt lgkmcnt(0)" ::: "memory");
; }
; DI void convw_phase(const Args& A, int l, LAS unsigned char* lds, int tid, int bid, int G) {
;     ...
;         r -= I_GU;
;         if (r < I_DN) {
;             const int f = r / ((DFF / 64) * 32); r -= f * (DFF / 64) * 32;
;             const int kb = r / 32, nb = r % 32;
;             transpose_item_wide(A.in[I_WD] + (size_t)(l * 2 + f) * DFF * DM, DM, DFF, nb * 32, wdn + (size_t)f * DM * DFF, nb * 32, kb * 64, scr, lane);
;             continue;
.LBB0_265:
	s_andn2_saveexec_b64 s[2:3], s[2:3]
	s_cbranch_execz .LBB0_267
	v_add_u32_e32 v0, 0xffffea00, v80
	s_movk_i32 s14, 0x57f
	v_cmp_lt_u32_e32 vcc, s14, v0
	v_readlane_b32 s36, v252, 10
	v_readlane_b32 s37, v252, 11
	v_cndmask_b32_e32 v2, 0, v212, vcc
	v_add_u32_e32 v0, v2, v0
	v_ashrrev_i16_e32 v2, 15, v0
	v_lshrrev_b16_e32 v2, 11, v2
	v_add_u16_e32 v2, v0, v2
	v_cndmask_b32_e64 v1, 0, 1, vcc
	v_ashrrev_i16_e32 v18, 5, v2
	v_and_b32_e32 v2, 0xffffffe0, v2
	v_sub_u16_e32 v2, v0, v2
	v_or_b32_e32 v3, s23, v1
	v_mov_b64_e32 v[0:1], s[36:37]
	s_mov_b32 s14, 0xb00000
	v_mad_i64_i32 v[32:33], s[14:15], v3, s14, v[0:1]
	v_lshlrev_b32_sdwa v0, v213, sext(v2) dst_sel:DWORD dst_unused:UNUSED_PAD src0_sel:DWORD src1_sel:WORD_0
	v_readlane_b32 s14, v252, 1
	v_cndmask_b32_e32 v146, 0, v214, vcc
	v_readlane_b32 s15, v252, 2
	v_ashrrev_i32_e32 v1, 31, v0
	v_lshlrev_b32_sdwa v18, v211, sext(v18) dst_sel:DWORD dst_unused:UNUSED_PAD src0_sel:DWORD src1_sel:WORD_0
	v_lshl_add_u64 v[2:3], s[14:15], 0, v[146:147]
	v_lshl_add_u64 v[32:33], v[0:1], 2, v[32:33]
	v_lshlrev_b32_e32 v146, 2, v4
	v_lshl_add_u64 v[36:37], v[32:33], 0, v[146:147]
	v_or_b32_e32 v32, v18, v7
	v_ashrrev_i32_e32 v33, 31, v32
	v_lshlrev_b64 v[32:33], 12, v[32:33]
	v_lshl_add_u64 v[32:33], v[36:37], 0, v[32:33]
	global_load_dwordx4 v[96:99], v[32:33], off nt
	v_or_b32_e32 v128, v18, v20
	v_ashrrev_i32_e32 v129, 31, v128
	v_lshlrev_b64 v[130:131], 12, v[128:129]
	v_lshl_add_u64 v[132:133], v[36:37], 0, v[130:131]
	global_load_dwordx4 v[100:103], v[132:133], off nt
	v_or_b32_e32 v134, v18, v21
	v_ashrrev_i32_e32 v135, 31, v134
	v_lshlrev_b64 v[136:137], 12, v[134:135]
	v_lshl_add_u64 v[138:139], v[36:37], 0, v[136:137]
	global_load_dwordx4 v[104:107], v[138:139], off nt
	v_or_b32_e32 v140, v18, v22
	v_ashrrev_i32_e32 v141, 31, v140
	v_lshlrev_b64 v[142:143], 12, v[140:141]
	v_lshl_add_u64 v[160:161], v[36:37], 0, v[142:143]
	global_load_dwordx4 v[108:111], v[160:161], off nt
	v_or_b32_e32 v162, v18, v23
	v_ashrrev_i32_e32 v163, 31, v162
	v_lshlrev_b64 v[164:165], 12, v[162:163]
	v_lshl_add_u64 v[166:167], v[36:37], 0, v[164:165]
	global_load_dwordx4 v[112:115], v[166:167], off nt
	v_or_b32_e32 v168, v18, v24
	v_ashrrev_i32_e32 v169, 31, v168
	v_lshlrev_b64 v[170:171], 12, v[168:169]
	v_lshl_add_u64 v[172:173], v[36:37], 0, v[170:171]
	global_load_dwordx4 v[116:119], v[172:173], off nt
	v_or_b32_e32 v174, v18, v25
	v_ashrrev_i32_e32 v175, 31, v174
	v_lshlrev_b64 v[176:177], 12, v[174:175]
	v_lshl_add_u64 v[178:179], v[36:37], 0, v[176:177]
	global_load_dwordx4 v[120:123], v[178:179], off nt
	v_or_b32_e32 v180, v18, v26
	v_ashrrev_i32_e32 v181, 31, v180
	v_lshlrev_b64 v[182:183], 12, v[180:181]
	v_lshl_add_u64 v[184:185], v[36:37], 0, v[182:183]
	global_load_dwordx4 v[124:127], v[184:185], off nt
	v_add_u32_e32 v1, v11, v13
	v_add_u32_e32 v19, 0x420, v1
	v_lshlrev_b32_e32 v146, 1, v6
	v_readlane_b32 s38, v252, 12
	v_readlane_b32 s39, v252, 13
	v_readlane_b32 s40, v252, 14
	v_readlane_b32 s41, v252, 15
	v_readlane_b32 s42, v252, 16
	v_readlane_b32 s43, v252, 17
	v_readlane_b32 s44, v252, 18
	v_readlane_b32 s45, v252, 19
	v_readlane_b32 s46, v252, 20
	v_readlane_b32 s47, v252, 21
	v_readlane_b32 s48, v252, 22
	v_readlane_b32 s49, v252, 23
	v_readlane_b32 s50, v252, 24
	v_readlane_b32 s51, v252, 25
	s_waitcnt vmcnt(7)
	ds_write2_b32 v1, v96, v97 offset1:1
	ds_write2_b32 v1, v98, v99 offset0:2 offset1:3
	s_waitcnt vmcnt(6)
	ds_write2_b32 v19, v100, v101 offset1:1
	v_add_u32_e32 v19, 0x428, v1
	ds_write2_b32 v19, v102, v103 offset1:1
	v_add_u32_e32 v19, 0x840, v1
	s_waitcnt vmcnt(5)
	ds_write2_b32 v19, v104, v105 offset1:1
	v_add_u32_e32 v19, 0x848, v1
	ds_write2_b32 v19, v106, v107 offset1:1
	v_add_u32_e32 v19, 0xc60, v1
	s_waitcnt vmcnt(4)
	ds_write2_b32 v19, v108, v109 offset1:1
	v_add_u32_e32 v19, 0xc68, v1
	ds_write2_b32 v19, v110, v111 offset1:1
	v_add_u32_e32 v19, 0x1080, v1
	s_waitcnt vmcnt(3)
	ds_write2_b32 v19, v112, v113 offset1:1
	v_add_u32_e32 v19, 0x1088, v1
	ds_write2_b32 v19, v114, v115 offset1:1
	v_add_u32_e32 v19, 0x14a0, v1
	s_waitcnt vmcnt(2)
	ds_write2_b32 v19, v116, v117 offset1:1
	v_add_u32_e32 v19, 0x14a8, v1
	ds_write2_b32 v19, v118, v119 offset1:1
	v_add_u32_e32 v19, 0x18c0, v1
	s_waitcnt vmcnt(1)
	ds_write2_b32 v19, v120, v121 offset1:1
	v_add_u32_e32 v19, 0x18c8, v1
	ds_write2_b32 v19, v122, v123 offset1:1
	v_add_u32_e32 v19, 0x1ce0, v1
	v_add_u32_e32 v1, 0x1ce8, v1
	s_waitcnt vmcnt(0)
	ds_write2_b32 v19, v124, v125 offset1:1
	ds_write2_b32 v1, v126, v127 offset1:1
	s_waitcnt lgkmcnt(0)
	v_ashrrev_i32_e32 v19, 31, v18
	v_lshl_add_u64 v[2:3], v[18:19], 1, v[2:3]
	ds_read2_b32 v[18:19], v27 offset0:33 offset1:41
	ds_read2_b32 v[36:37], v27 offset1:8
	ds_read2_b32 v[38:39], v27 offset0:66 offset1:74
	ds_read2_b32 v[40:41], v27 offset0:99 offset1:107
	ds_read2_b32 v[42:43], v27 offset0:132 offset1:140
	ds_read2_b32 v[44:45], v27 offset0:165 offset1:173
	ds_read2_b32 v[46:47], v27 offset0:198 offset1:206
	ds_read2_b32 v[48:49], v27 offset0:231 offset1:239
	v_or_b32_e32 v1, v0, v7
	v_mul_i32_i24_e32 v50, 0xb00, v1
	v_lshl_add_u64 v[2:3], v[2:3], 0, v[146:147]
	v_ashrrev_i32_e32 v51, 31, v50
	v_or_b32_e32 v1, v0, v20
	s_waitcnt lgkmcnt(6)
	v_cvt_pk_bf16_f32 v32, v36, v18
	s_waitcnt lgkmcnt(4)
	v_cvt_pk_bf16_f32 v33, v38, v40
	s_waitcnt lgkmcnt(2)
	v_cvt_pk_bf16_f32 v34, v42, v44
	s_waitcnt lgkmcnt(0)
	v_cvt_pk_bf16_f32 v35, v46, v48
	v_lshl_add_u64 v[50:51], v[50:51], 1, v[2:3]
	v_mul_i32_i24_e32 v18, 0xb00, v1
	global_store_dwordx4 v[50:51], v[32:35], off
	v_or_b32_e32 v1, v0, v21
	v_mul_i32_i24_e32 v50, 0xb00, v1
	v_cvt_pk_bf16_f32 v32, v37, v19
	v_ashrrev_i32_e32 v19, 31, v18
	v_cvt_pk_bf16_f32 v33, v39, v41
	v_cvt_pk_bf16_f32 v34, v43, v45
	v_cvt_pk_bf16_f32 v35, v47, v49
	v_lshl_add_u64 v[18:19], v[18:19], 1, v[2:3]
	global_store_dwordx4 v[18:19], v[32:35], off
	ds_read2_b32 v[18:19], v27 offset0:16 offset1:24
	ds_read2_b32 v[36:37], v27 offset0:49 offset1:57
	ds_read2_b32 v[38:39], v27 offset0:82 offset1:90
	ds_read2_b32 v[40:41], v27 offset0:115 offset1:123
	ds_read2_b32 v[42:43], v27 offset0:148 offset1:156
	ds_read2_b32 v[44:45], v27 offset0:181 offset1:189
	ds_read2_b32 v[46:47], v27 offset0:214 offset1:222
	ds_read2_b32 v[48:49], v27 offset0:247 offset1:255
	v_or_b32_e32 v0, v0, v22
	v_ashrrev_i32_e32 v51, 31, v50
	v_mul_i32_i24_e32 v0, 0xb00, v0
	s_waitcnt lgkmcnt(6)
	v_cvt_pk_bf16_f32 v32, v18, v36
	s_waitcnt lgkmcnt(4)
	v_cvt_pk_bf16_f32 v33, v38, v40
	s_waitcnt lgkmcnt(2)
	v_cvt_pk_bf16_f32 v34, v42, v44
	s_waitcnt lgkmcnt(0)
	v_cvt_pk_bf16_f32 v35, v46, v48
	v_lshl_add_u64 v[50:51], v[50:51], 1, v[2:3]
	v_ashrrev_i32_e32 v1, 31, v0
	global_store_dwordx4 v[50:51], v[32:35], off
	v_lshl_add_u64 v[0:1], v[0:1], 1, v[2:3]
	s_nop 0
	v_cvt_pk_bf16_f32 v32, v19, v37
	v_cvt_pk_bf16_f32 v33, v39, v41
	v_cvt_pk_bf16_f32 v34, v43, v45
	v_cvt_pk_bf16_f32 v35, v47, v49
	global_store_dwordx4 v[0:1], v[32:35], off
	s_waitcnt lgkmcnt(0)

; #define LAS __attribute__((address_space(3)))
; DI unsigned pk2(float lo, float hi) { f32x2 v = {lo, hi}; bf16x2_t b = __builtin_convertvector(v, bf16x2_t); return __builtin_bit_cast(unsigned, b); }
; DI void transpose_item_wide(const float* W, int ldw, int K, int src0, bf16* WT, int n0, int k0, LAS float* scr, int lane) {
;     const int c4 = lane & 7, kr = lane >> 3;
; #pragma unroll
;     for (int i = 0; i < 8; ++i) { const int kk = kr + 8 * i; const f32x4 v = *(const f32x4*)(W + (size_t)(k0 + kk) * ldw + src0 + 4 * c4);
;         LAS float* d = scr + kk * 33 + 4 * c4; d[0] = v.x; d[1] = v.y; d[2] = v.z; d[3] = v.w; }
;     asm volatile("s_waitcnt lgkmcnt(0)" ::: "memory");
;     const int c = lane & 7;
; #pragma unroll
;     for (int j = 0; j < 4; ++j) {
;         const int n = (lane >> 3) + 8 * j; const LAS float* sp = scr + (8 * c) * 33 + n;
;         u32x4 o; o.x = pk2(sp[0 * 33], sp[1 * 33]); o.y = pk2(sp[2 * 33], sp[3 * 33]); o.z = pk2(sp[4 * 33], sp[5 * 33]); o.w = pk2(sp[6 * 33], sp[7 * 33]);
;         *(u32x4*)(WT + (size_t)(n0 + n) * K + k0 + 8 * c) = o;
;     }
;     asm volatile("s_waitcnt lgkmcnt(0)" ::: "memory");
; }
; DI void convw_phase(const Args& A, int l, LAS unsigned char* lds, int tid, int bid, int G) {
;     ...
;         if (r < I_GU) {
;             const int f = r / (16 * (NGU / 32)); r -= f * 16 * (NGU / 32);
;             const int kb = r / (NGU / 32), nb = r % (NGU / 32), n0 = nb * 32, pn = n0 >> 8, cc = n0 & 255;
;             const float* src = (cc < 128 ? A.in[I_WG] : A.in[I_WU]) + (size_t)(l * 2 + f) * DM * DFF;
;             transpose_item_wide(src, DFF, DM, 128 * pn + (cc & 127), wgu + (size_t)f * NGU * DM, n0, kb * 64, scr, lane);
;             continue;
.LBB0_268:
	s_andn2_saveexec_b64 s[2:3], s[8:9]
	s_cbranch_execz .LBB0_245
	s_mov_b32 s8, 0x2e8ba2e9
	v_mul_hi_i32 v0, v80, s8
	v_lshrrev_b32_e32 v1, 31, v0
	v_ashrrev_i32_e32 v0, 9, v0
	v_add_u32_e32 v2, v0, v1
	v_mul_i32_i24_e32 v0, 0xfffff500, v2
	v_add_u32_e32 v0, v0, v80
	v_mul_hi_i32 v1, v0, s8
	v_lshrrev_b32_e32 v3, 31, v1
	v_ashrrev_i32_e32 v1, 5, v1
	v_add_u32_e32 v3, v1, v3
	s_movk_i32 s8, 0xb0
	v_mul_lo_u32 v1, v3, s8
	v_sub_u32_e32 v32, v0, v1
	v_and_b32_e32 v0, 4, v32
	v_cmp_eq_u32_e32 vcc, 0, v0
	v_readlane_b32 s8, v253, 28
	v_readlane_b32 s9, v253, 29
	v_cndmask_b32_e64 v146, v215, 64, vcc
	v_add_u32_e32 v18, s23, v2
	v_lshl_add_u64 v[0:1], s[8:9], 0, v[146:147]
	global_load_dwordx2 v[0:1], v[0:1], off
	s_mov_b32 s14, 0xb00000
	v_lshlrev_b32_e32 v31, 5, v32
	v_lshlrev_b32_e32 v146, 2, v4
	v_or_b32_e32 v48, v31, v7
	v_ashrrev_i32_e32 v49, 31, v48
	v_lshlrev_b64 v[48:49], 11, v[48:49]
	s_waitcnt vmcnt(0)
	v_mad_i64_i32 v[18:19], s[8:9], v18, s14, v[0:1]
	v_lshlrev_b32_e32 v0, 4, v32
	v_and_b32_e32 v1, 0x60, v31
	s_movk_i32 s8, 0xff80
	v_and_or_b32 v32, v0, s8, v1
	v_readlane_b32 s8, v251, 63
	v_readlane_b32 s9, v252, 0
	v_ashrrev_i32_e32 v33, 31, v32
	v_lshl_add_u64 v[18:19], v[32:33], 2, v[18:19]
	v_mov_b64_e32 v[0:1], s[8:9]
	v_mad_i64_i32 v[0:1], s[8:9], v2, s14, v[0:1]
	v_lshlrev_b32_e32 v2, 6, v3
	v_lshl_add_u64 v[18:19], v[18:19], 0, v[146:147]
	v_or_b32_e32 v3, v2, v7
	s_movk_i32 s14, 0x2c00
	v_mad_i64_i32 v[32:33], s[8:9], v3, s14, v[18:19]
	global_load_dwordx4 v[96:99], v[32:33], off nt
	v_or_b32_e32 v128, v2, v20
	v_mad_i64_i32 v[130:131], s[8:9], v128, s14, v[18:19]
	global_load_dwordx4 v[100:103], v[130:131], off nt
	v_or_b32_e32 v132, v2, v21
	v_mad_i64_i32 v[134:135], s[8:9], v132, s14, v[18:19]
	global_load_dwordx4 v[104:107], v[134:135], off nt
	v_or_b32_e32 v136, v2, v22
	v_mad_i64_i32 v[138:139], s[8:9], v136, s14, v[18:19]
	global_load_dwordx4 v[108:111], v[138:139], off nt
	v_or_b32_e32 v140, v2, v23
	v_mad_i64_i32 v[142:143], s[8:9], v140, s14, v[18:19]
	global_load_dwordx4 v[112:115], v[142:143], off nt
	v_or_b32_e32 v160, v2, v24
	v_mad_i64_i32 v[162:163], s[8:9], v160, s14, v[18:19]
	global_load_dwordx4 v[116:119], v[162:163], off nt
	v_or_b32_e32 v164, v2, v25
	v_mad_i64_i32 v[166:167], s[8:9], v164, s14, v[18:19]
	global_load_dwordx4 v[120:123], v[166:167], off nt
	v_or_b32_e32 v168, v2, v26
	v_mad_i64_i32 v[170:171], s[8:9], v168, s14, v[18:19]
	global_load_dwordx4 v[124:127], v[170:171], off nt
	v_add_u32_e32 v3, v11, v13
	v_add_u32_e32 v36, 0x420, v3
	v_lshlrev_b32_e32 v146, 1, v6
	s_waitcnt vmcnt(7)
	ds_write2_b32 v3, v96, v97 offset1:1
	ds_write2_b32 v3, v98, v99 offset0:2 offset1:3
	s_waitcnt vmcnt(6)
	ds_write2_b32 v36, v100, v101 offset1:1
	v_add_u32_e32 v32, 0x428, v3
	ds_write2_b32 v32, v102, v103 offset1:1
	v_add_u32_e32 v36, 0x840, v3
	s_waitcnt vmcnt(5)
	ds_write2_b32 v36, v104, v105 offset1:1
	v_add_u32_e32 v32, 0x848, v3
	ds_write2_b32 v32, v106, v107 offset1:1
	v_add_u32_e32 v36, 0xc60, v3
	s_waitcnt vmcnt(4)
	ds_write2_b32 v36, v108, v109 offset1:1
	v_add_u32_e32 v32, 0xc68, v3
	ds_write2_b32 v32, v110, v111 offset1:1
	v_add_u32_e32 v36, 0x1080, v3
	s_waitcnt vmcnt(3)
	ds_write2_b32 v36, v112, v113 offset1:1
	v_add_u32_e32 v32, 0x1088, v3
	ds_write2_b32 v32, v114, v115 offset1:1
	v_add_u32_e32 v36, 0x14a0, v3
	s_waitcnt vmcnt(2)
	ds_write2_b32 v36, v116, v117 offset1:1
	v_add_u32_e32 v32, 0x14a8, v3
	ds_write2_b32 v32, v118, v119 offset1:1
	v_add_u32_e32 v36, 0x18c0, v3
	s_waitcnt vmcnt(1)
	ds_write2_b32 v36, v120, v121 offset1:1
	v_add_u32_e32 v32, 0x18c8, v3
	ds_write2_b32 v32, v122, v123 offset1:1
	v_add_u32_e32 v18, 0x1ce0, v3
	v_add_u32_e32 v3, 0x1ce8, v3
	s_waitcnt vmcnt(0)
	ds_write2_b32 v18, v124, v125 offset1:1
	ds_write2_b32 v3, v126, v127 offset1:1
	s_waitcnt lgkmcnt(0)
	ds_read2_b32 v[32:33], v27 offset0:33 offset1:41
	ds_read2_b32 v[34:35], v27 offset1:8
	ds_read2_b32 v[36:37], v27 offset0:66 offset1:74
	ds_read2_b32 v[38:39], v27 offset0:99 offset1:107
	ds_read2_b32 v[40:41], v27 offset0:132 offset1:140
	ds_read2_b32 v[42:43], v27 offset0:165 offset1:173
	ds_read2_b32 v[44:45], v27 offset0:198 offset1:206
	ds_read2_b32 v[46:47], v27 offset0:231 offset1:239
	v_ashrrev_i32_e32 v3, 31, v2
	v_lshl_add_u64 v[0:1], v[2:3], 1, v[0:1]
	v_lshl_add_u64 v[18:19], v[0:1], 0, v[146:147]
	s_waitcnt lgkmcnt(6)
	v_cvt_pk_bf16_f32 v0, v34, v32
	s_waitcnt lgkmcnt(4)
	v_cvt_pk_bf16_f32 v1, v36, v38
	s_waitcnt lgkmcnt(2)
	v_cvt_pk_bf16_f32 v2, v40, v42
	s_waitcnt lgkmcnt(0)
	v_cvt_pk_bf16_f32 v3, v44, v46
	v_lshl_add_u64 v[48:49], v[18:19], 0, v[48:49]
	v_or_b32_e32 v32, v31, v20
	global_store_dwordx4 v[48:49], v[0:3], off
	v_or_b32_e32 v48, v31, v21
	v_ashrrev_i32_e32 v49, 31, v48
	v_cvt_pk_bf16_f32 v0, v35, v33
	v_ashrrev_i32_e32 v33, 31, v32
	v_lshlrev_b64 v[32:33], 11, v[32:33]
	v_cvt_pk_bf16_f32 v1, v37, v39
	v_cvt_pk_bf16_f32 v2, v41, v43
	v_cvt_pk_bf16_f32 v3, v45, v47
	v_lshl_add_u64 v[32:33], v[18:19], 0, v[32:33]
	global_store_dwordx4 v[32:33], v[0:3], off
	ds_read2_b32 v[32:33], v27 offset0:49 offset1:57
	ds_read2_b32 v[34:35], v27 offset0:16 offset1:24
	ds_read2_b32 v[36:37], v27 offset0:82 offset1:90
	ds_read2_b32 v[38:39], v27 offset0:115 offset1:123
	ds_read2_b32 v[40:41], v27 offset0:148 offset1:156
	ds_read2_b32 v[42:43], v27 offset0:181 offset1:189
	ds_read2_b32 v[44:45], v27 offset0:214 offset1:222
	ds_read2_b32 v[46:47], v27 offset0:247 offset1:255
	v_lshlrev_b64 v[48:49], 11, v[48:49]
	s_waitcnt lgkmcnt(6)
	v_cvt_pk_bf16_f32 v0, v34, v32
	s_waitcnt lgkmcnt(4)
	v_cvt_pk_bf16_f32 v1, v36, v38
	s_waitcnt lgkmcnt(2)
	v_cvt_pk_bf16_f32 v2, v40, v42
	s_waitcnt lgkmcnt(0)
	v_cvt_pk_bf16_f32 v3, v44, v46
	v_lshl_add_u64 v[48:49], v[18:19], 0, v[48:49]
	v_or_b32_e32 v32, v31, v22
	global_store_dwordx4 v[48:49], v[0:3], off
	s_nop 1
	v_cvt_pk_bf16_f32 v0, v35, v33
	v_ashrrev_i32_e32 v33, 31, v32
	v_lshlrev_b64 v[32:33], 11, v[32:33]
	v_cvt_pk_bf16_f32 v1, v37, v39
	v_cvt_pk_bf16_f32 v2, v41, v43
	v_cvt_pk_bf16_f32 v3, v45, v47
	v_lshl_add_u64 v[18:19], v[18:19], 0, v[32:33]
	global_store_dwordx4 v[18:19], v[0:3], off
	s_waitcnt lgkmcnt(0)
	s_branch .LBB0_245

; #define LAS __attribute__((address_space(3)))
; DI unsigned pk2(float lo, float hi) { f32x2 v = {lo, hi}; bf16x2_t b = __builtin_convertvector(v, bf16x2_t); return __builtin_bit_cast(unsigned, b); }
; DI void transpose_item_wide(const float* W, int ldw, int K, int src0, bf16* WT, int n0, int k0, LAS float* scr, int lane) {
;     const int c4 = lane & 7, kr = lane >> 3;
; #pragma unroll
;     for (int i = 0; i < 8; ++i) { const int kk = kr + 8 * i; const f32x4 v = *(const f32x4*)(W + (size_t)(k0 + kk) * ldw + src0 + 4 * c4);
;         LAS float* d = scr + kk * 33 + 4 * c4; d[0] = v.x; d[1] = v.y; d[2] = v.z; d[3] = v.w; }
;     asm volatile("s_waitcnt lgkmcnt(0)" ::: "memory");
;     const int c = lane & 7;
; #pragma unroll
;     for (int j = 0; j < 4; ++j) {
;         const int n = (lane >> 3) + 8 * j; const LAS float* sp = scr + (8 * c) * 33 + n;
;         u32x4 o; o.x = pk2(sp[0 * 33], sp[1 * 33]); o.y = pk2(sp[2 * 33], sp[3 * 33]); o.z = pk2(sp[4 * 33], sp[5 * 33]); o.w = pk2(sp[6 * 33], sp[7 * 33]);
;         *(u32x4*)(WT + (size_t)(n0 + n) * K + k0 + 8 * c) = o;
;     }
;     asm volatile("s_waitcnt lgkmcnt(0)" ::: "memory");
; }
; DI void convw_phase(const Args& A, int l, LAS unsigned char* lds, int tid, int bid, int G) {
;     ...
;         if (r < I_GU) {
;             const int f = r / (16 * (NGU / 32)); r -= f * 16 * (NGU / 32);
;             const int kb = r / (NGU / 32), nb = r % (NGU / 32), n0 = nb * 32, pn = n0 >> 8, cc = n0 & 255;
;             const float* src = (cc < 128 ? A.in[I_WG] : A.in[I_WU]) + (size_t)(l * 2 + f) * DM * DFF;
;             transpose_item_wide(src, DFF, DM, 128 * pn + (cc & 127), wgu + (size_t)f * NGU * DM, n0, kb * 64, scr, lane);
;             continue;
.LBB0_978:
	s_andn2_saveexec_b64 s[4:5], s[4:5]
	s_cbranch_execz .LBB0_955
	s_mov_b32 s6, 0x2e8ba2e9
	v_mul_hi_i32 v0, v7, s6
	v_lshrrev_b32_e32 v1, 31, v0
	v_ashrrev_i32_e32 v0, 9, v0
	v_add_u32_e32 v2, v0, v1
	v_mul_i32_i24_e32 v0, 0xfffff500, v2
	v_add_u32_e32 v0, v0, v7
	v_mul_hi_i32 v1, v0, s6
	v_lshrrev_b32_e32 v3, 31, v1
	v_ashrrev_i32_e32 v1, 5, v1
	v_add_u32_e32 v3, v1, v3
	s_movk_i32 s6, 0xb0
	v_mul_lo_u32 v1, v3, s6
	v_sub_u32_e32 v33, v0, v1
	v_and_b32_e32 v0, 4, v33
	v_cmp_eq_u32_e32 vcc, 0, v0
	s_mov_b32 s8, 0xb00000
	v_lshlrev_b32_e32 v32, 5, v33
	v_cndmask_b32_e64 v146, v215, 64, vcc
	v_lshl_add_u64 v[0:1], s[30:31], 0, v[146:147]
	global_load_dwordx2 v[0:1], v[0:1], off
	v_lshlrev_b32_e32 v146, 2, v4
	v_or_b32_e32 v50, v32, v9
	v_ashrrev_i32_e32 v51, 31, v50
	v_lshlrev_b64 v[50:51], 11, v[50:51]
	s_waitcnt vmcnt(0)
	v_mad_i64_i32 v[18:19], s[6:7], v2, s8, v[0:1]
	v_lshlrev_b32_e32 v0, 4, v33
	v_and_b32_e32 v1, 0x60, v32
	s_movk_i32 s6, 0xff80
	v_and_or_b32 v34, v0, s6, v1
	v_readlane_b32 s6, v251, 63
	v_readlane_b32 s7, v252, 0
	v_ashrrev_i32_e32 v35, 31, v34
	v_lshl_add_u64 v[18:19], v[34:35], 2, v[18:19]
	v_mov_b64_e32 v[0:1], s[6:7]
	v_mad_i64_i32 v[0:1], s[6:7], v2, s8, v[0:1]
	v_lshlrev_b32_e32 v2, 6, v3
	v_lshl_add_u64 v[18:19], v[18:19], 0, v[146:147]
	v_or_b32_e32 v3, v2, v9
	s_movk_i32 s8, 0x2c00
	v_mad_i64_i32 v[34:35], s[6:7], v3, s8, v[18:19]
	global_load_dwordx4 v[96:99], v[34:35], off nt
	v_or_b32_e32 v128, v2, v22
	v_mad_i64_i32 v[130:131], s[6:7], v128, s8, v[18:19]
	global_load_dwordx4 v[100:103], v[130:131], off nt
	v_or_b32_e32 v132, v2, v23
	v_mad_i64_i32 v[134:135], s[6:7], v132, s8, v[18:19]
	global_load_dwordx4 v[104:107], v[134:135], off nt
	v_or_b32_e32 v136, v2, v24
	v_mad_i64_i32 v[138:139], s[6:7], v136, s8, v[18:19]
	global_load_dwordx4 v[108:111], v[138:139], off nt
	v_or_b32_e32 v140, v2, v25
	v_mad_i64_i32 v[142:143], s[6:7], v140, s8, v[18:19]
	global_load_dwordx4 v[112:115], v[142:143], off nt
	v_or_b32_e32 v160, v2, v26
	v_mad_i64_i32 v[162:163], s[6:7], v160, s8, v[18:19]
	global_load_dwordx4 v[116:119], v[162:163], off nt
	v_or_b32_e32 v164, v2, v27
	v_mad_i64_i32 v[166:167], s[6:7], v164, s8, v[18:19]
	global_load_dwordx4 v[120:123], v[166:167], off nt
	v_or_b32_e32 v168, v2, v28
	v_mad_i64_i32 v[170:171], s[6:7], v168, s8, v[18:19]
	global_load_dwordx4 v[124:127], v[170:171], off nt
	v_add_u32_e32 v3, v11, v21
	v_lshlrev_b32_e32 v146, 1, v6
	s_waitcnt vmcnt(7)
	ds_write2_b32 v3, v96, v97 offset1:1
	ds_write2_b32 v3, v98, v99 offset0:2 offset1:3
	v_add_u32_e32 v33, 0x420, v3
	s_waitcnt vmcnt(6)
	ds_write2_b32 v33, v100, v101 offset1:1
	v_add_u32_e32 v33, 0x428, v3
	ds_write2_b32 v33, v102, v103 offset1:1
	v_add_u32_e32 v33, 0x840, v3
	s_waitcnt vmcnt(5)
	ds_write2_b32 v33, v104, v105 offset1:1
	v_add_u32_e32 v33, 0x848, v3
	ds_write2_b32 v33, v106, v107 offset1:1
	v_add_u32_e32 v33, 0xc60, v3
	s_waitcnt vmcnt(4)
	ds_write2_b32 v33, v108, v109 offset1:1
	v_add_u32_e32 v33, 0xc68, v3
	ds_write2_b32 v33, v110, v111 offset1:1
	v_add_u32_e32 v33, 0x1080, v3
	s_waitcnt vmcnt(3)
	ds_write2_b32 v33, v112, v113 offset1:1
	v_add_u32_e32 v33, 0x1088, v3
	ds_write2_b32 v33, v114, v115 offset1:1
	v_add_u32_e32 v33, 0x14a0, v3
	s_waitcnt vmcnt(2)
	ds_write2_b32 v33, v116, v117 offset1:1
	v_add_u32_e32 v33, 0x14a8, v3
	ds_write2_b32 v33, v118, v119 offset1:1
	v_add_u32_e32 v33, 0x18c0, v3
	s_waitcnt vmcnt(1)
	ds_write2_b32 v33, v120, v121 offset1:1
	v_add_u32_e32 v33, 0x18c8, v3
	ds_write2_b32 v33, v122, v123 offset1:1
	v_add_u32_e32 v18, 0x1ce0, v3
	v_add_u32_e32 v3, 0x1ce8, v3
	s_waitcnt vmcnt(0)
	ds_write2_b32 v18, v124, v125 offset1:1
	ds_write2_b32 v3, v126, v127 offset1:1
	s_waitcnt lgkmcnt(0)
	ds_read2_b32 v[34:35], v29 offset0:33 offset1:41
	ds_read2_b32 v[36:37], v29 offset1:8
	ds_read2_b32 v[38:39], v29 offset0:66 offset1:74
	ds_read2_b32 v[40:41], v29 offset0:99 offset1:107
	ds_read2_b32 v[42:43], v29 offset0:132 offset1:140
	ds_read2_b32 v[44:45], v29 offset0:165 offset1:173
	ds_read2_b32 v[46:47], v29 offset0:198 offset1:206
	ds_read2_b32 v[48:49], v29 offset0:231 offset1:239
	v_ashrrev_i32_e32 v3, 31, v2
	v_lshl_add_u64 v[0:1], v[2:3], 1, v[0:1]
	v_lshl_add_u64 v[18:19], v[0:1], 0, v[146:147]
	s_waitcnt lgkmcnt(6)
	v_cvt_pk_bf16_f32 v0, v36, v34
	s_waitcnt lgkmcnt(4)
	v_cvt_pk_bf16_f32 v1, v38, v40
	s_waitcnt lgkmcnt(2)
	v_cvt_pk_bf16_f32 v2, v42, v44
	s_waitcnt lgkmcnt(0)
	v_cvt_pk_bf16_f32 v3, v46, v48
	v_lshl_add_u64 v[50:51], v[18:19], 0, v[50:51]
	v_or_b32_e32 v34, v32, v22
	global_store_dwordx4 v[50:51], v[0:3], off
	v_or_b32_e32 v50, v32, v23
	v_ashrrev_i32_e32 v51, 31, v50
	v_cvt_pk_bf16_f32 v0, v37, v35
	v_ashrrev_i32_e32 v35, 31, v34
	v_lshlrev_b64 v[34:35], 11, v[34:35]
	v_cvt_pk_bf16_f32 v1, v39, v41
	v_cvt_pk_bf16_f32 v2, v43, v45
	v_cvt_pk_bf16_f32 v3, v47, v49
	v_lshl_add_u64 v[34:35], v[18:19], 0, v[34:35]
	global_store_dwordx4 v[34:35], v[0:3], off
	ds_read2_b32 v[34:35], v29 offset0:49 offset1:57
	ds_read2_b32 v[36:37], v29 offset0:16 offset1:24
	ds_read2_b32 v[38:39], v29 offset0:82 offset1:90
	ds_read2_b32 v[40:41], v29 offset0:115 offset1:123
	ds_read2_b32 v[42:43], v29 offset0:148 offset1:156
	ds_read2_b32 v[44:45], v29 offset0:181 offset1:189
	ds_read2_b32 v[46:47], v29 offset0:214 offset1:222
	ds_read2_b32 v[48:49], v29 offset0:247 offset1:255
	v_or_b32_e32 v32, v32, v24
	v_lshlrev_b64 v[50:51], 11, v[50:51]
	v_ashrrev_i32_e32 v33, 31, v32
	s_waitcnt lgkmcnt(6)
	v_cvt_pk_bf16_f32 v0, v36, v34
	s_waitcnt lgkmcnt(4)
	v_cvt_pk_bf16_f32 v1, v38, v40
	s_waitcnt lgkmcnt(2)
	v_cvt_pk_bf16_f32 v2, v42, v44
	s_waitcnt lgkmcnt(0)
	v_cvt_pk_bf16_f32 v3, v46, v48
	v_lshl_add_u64 v[50:51], v[18:19], 0, v[50:51]
	v_lshlrev_b64 v[32:33], 11, v[32:33]
	global_store_dwordx4 v[50:51], v[0:3], off
	v_lshl_add_u64 v[18:19], v[18:19], 0, v[32:33]
	s_nop 0
	v_cvt_pk_bf16_f32 v0, v37, v35
	v_cvt_pk_bf16_f32 v1, v39, v41
	v_cvt_pk_bf16_f32 v2, v43, v45
	v_cvt_pk_bf16_f32 v3, v47, v49
	global_store_dwordx4 v[18:19], v[0:3], off
	s_waitcnt lgkmcnt(0)
	s_branch .LBB0_955
